# same-XCC grid barrier for XCC-local phase seams (st 0,1,2,5,6,7,8,9), row passes remapped to XCC-aligned rows; plus deferred weight conversion
# speedup vs baseline: 1.0138x; 1.0027x over previous
.LBB0_8:
	s_or_b64 exec, exec, s[2:3]
	s_waitcnt lgkmcnt(0)
	s_barrier
	s_load_dwordx2 s[44:45], s[0:1], 0xd8
	s_waitcnt lgkmcnt(0)
	s_cmp_ge_i32 s44, s45
	s_cbranch_scc1 .LBB0_864
	s_load_dword s2, s[0:1], 0xe0
	s_lshl_b32 s64, s33, 3
	s_load_dwordx2 s[0:1], s[0:1], 0xc8
	s_lshl_b32 s28, s33, 9
	v_lshrrev_b32_e32 v2, 20, v0
	s_waitcnt lgkmcnt(0)
	s_cmp_lg_u32 s2, 0
	s_cselect_b64 s[30:31], -1, 0
	v_writelane_b32 v253, s0, 5
	s_add_i32 s26, s44, 1
	v_lshrrev_b32_e32 v0, 10, v0
	v_writelane_b32 v253, s1, 6
	s_and_b32 s0, s33, 7
	s_cmp_eq_u32 s0, 0
	s_cselect_b64 s[0:1], -1, 0
	v_writelane_b32 v253, s0, 7
	s_ashr_i32 s53, s33, 31
	v_or_b32_e32 v0, v0, v2
	v_writelane_b32 v253, s1, 8
	s_lshr_b32 s0, s53, 29
	s_add_i32 s0, s33, s0
	s_ashr_i32 s0, s0, 3
	s_cmpk_lg_i32 s33, 0x100
	v_writelane_b32 v253, s0, 9
	s_cselect_b64 s[0:1], -1, 0
	v_writelane_b32 v253, s0, 10
	v_mov_b32_e32 v145, 0
	v_mov_b32_e32 v247, 0x358637bd
	v_writelane_b32 v253, s1, 11
	s_add_u32 s0, s78, 0xdc00000
	s_addc_u32 s1, s79, 0
	v_writelane_b32 v253, s0, 12
	v_mov_b32_e32 v236, 0x2000
	v_mov_b32_e32 v237, 1
	v_writelane_b32 v253, s1, 13
	s_add_u32 s0, s78, 0xdd00000
	s_addc_u32 s1, s79, 0
	v_writelane_b32 v253, s0, 14
	v_mov_b32_e32 v239, 0x9000
	v_mov_b32_e32 v245, 0x3e000000
	v_writelane_b32 v253, s1, 15
	s_add_u32 s0, s78, 0xde00000
	s_addc_u32 s1, s79, 0
	v_writelane_b32 v253, s0, 16
	s_movk_i32 s65, 0x88
	s_mov_b32 s95, 0x20000
	v_writelane_b32 v253, s1, 17
	s_add_u32 s0, s78, 0xda00000
	s_addc_u32 s1, s79, 0
	s_cmp_gt_i32 s33, 64
	v_writelane_b32 v253, s0, 18
	s_cselect_b32 s3, 64, 0
	s_ashr_i32 s29, s28, 31
	v_writelane_b32 v253, s1, 19
	s_sub_i32 s0, s33, s3
	s_lshl_b32 s1, s0, 3
	s_lshl_b32 s0, s0, 9
	v_writelane_b32 v253, s1, 20
	s_cmp_lt_i32 s2, 0
	v_writelane_b32 v253, s0, 21
	s_cselect_b64 s[0:1], -1, 0
	v_writelane_b32 v253, s0, 22
	s_mov_b32 s54, 0x9000
	s_movk_i32 s66, 0x1000
	v_writelane_b32 v253, s1, 23
	s_add_u32 s0, s78, 0x26400000
	v_writelane_b32 v253, s0, 24
	s_addc_u32 s0, s79, 0
	s_add_u32 s34, s78, 0x26400200
	s_addc_u32 s35, s79, 0
	s_add_u32 s36, s78, 0x26400400
	s_addc_u32 s37, s79, 0
	s_add_u32 s24, s78, 0x26400500
	s_addc_u32 s25, s79, 0
	s_add_u32 s16, s78, 0x26400600
	s_addc_u32 s17, s79, 0
	s_add_u32 s18, s78, 0x26400700
	s_addc_u32 s19, s79, 0
	s_add_u32 s20, s78, 0x26400800
	s_addc_u32 s21, s79, 0
	s_add_u32 s22, s78, 0x26400900
	s_addc_u32 s23, s79, 0
	s_add_u32 s42, s78, 0x26400a00
	s_addc_u32 s43, s79, 0
	s_add_u32 s46, s78, 0x26400b00
	s_addc_u32 s47, s79, 0
	s_add_u32 s48, s78, 0x26400c00
	s_addc_u32 s49, s79, 0
	s_add_u32 s60, s78, 0x26400d00
	s_addc_u32 s61, s79, 0
	s_add_u32 s62, s78, 0x26400e00
	s_addc_u32 s63, s79, 0
	s_add_u32 s72, s78, 0x26400f00
	s_addc_u32 s73, s79, 0
	s_add_u32 s82, s78, 0x26401000
	s_addc_u32 s83, s79, 0
	s_add_u32 s84, s78, 0x26401100
	s_addc_u32 s85, s79, 0
	s_add_u32 s86, s78, 0x26401200
	s_addc_u32 s87, s79, 0
	s_add_u32 s88, s78, 0x26401300
	s_addc_u32 s89, s79, 0
	v_writelane_b32 v253, s0, 25
	s_add_u32 s0, s78, 0x26403400
	s_addc_u32 s1, s79, 0
	v_writelane_b32 v253, s0, 26
	s_movk_i32 s69, 0x300
	s_movk_i32 s68, 0x2000
	v_writelane_b32 v253, s1, 27
	s_add_u32 s0, s78, 0x26403500
	s_addc_u32 s1, s79, 0
	s_abs_i32 s2, s33
	v_cvt_f32_u32_e32 v1, s2
	v_writelane_b32 v253, s0, 28
	s_mov_b32 s59, 0x12000
	s_mov_b32 s67, 0x24000
	v_rcp_iflag_f32_e32 v1, v1
	v_writelane_b32 v253, s1, 29
	s_movk_i32 s0, 0x3ff
	v_and_or_b32 v0, v0, s0, v244
	v_mul_f32_e32 v1, 0x4f7ffffe, v1
	v_cvt_u32_f32_e32 v1, v1
	s_sub_i32 s0, 0, s2
	s_mov_b32 s81, 0x2081cea
	s_mov_b32 s74, 0x36000
	v_readfirstlane_b32 s1, v1
	s_mul_i32 s0, s0, s1
	s_mul_hi_u32 s0, s1, s0
	s_add_i32 s0, s1, s0
	v_writelane_b32 v253, s0, 30
	s_mul_hi_u32 s0, s0, 0x5c0
	s_mul_i32 s0, s0, s2
	s_sub_i32 s0, 0x5c0, s0
	s_sub_i32 s1, s0, s2
	s_cmp_ge_u32 s0, s2
	s_cselect_b32 s0, s1, s0
	s_sub_i32 s1, s0, s2
	s_cmp_ge_u32 s0, s2
	v_writelane_b32 v253, s2, 31
	s_cselect_b32 s0, s1, s0
	v_writelane_b32 v253, s0, 32
	s_lshl_b32 s0, s33, 12
	s_lshl_b32 s1, s3, 12
	v_writelane_b32 v253, s3, 33
	s_sub_i32 s0, s0, s1
	v_writelane_b32 v253, s0, 34
	s_mul_i32 s0, s33, 0x11000
	s_mul_hi_i32 s1, s28, 0x88
	v_writelane_b32 v253, s0, 35
	s_movk_i32 s2, 0x3000
	s_mov_b32 s3, 0x22000000
	v_writelane_b32 v253, s1, 36
	s_lshl_b32 s0, s33, 4
	v_writelane_b32 v253, s0, 37
	s_lshl_b32 s0, s33, 10
	v_writelane_b32 v253, s0, 38
	s_lshl_b32 s0, s33, 11
	v_writelane_b32 v253, s0, 39
	s_add_i32 s0, 0, 0x2020c
	v_writelane_b32 v253, s0, 40
	s_add_i32 s0, 0, 0x20208
	v_writelane_b32 v253, s0, 41
	s_add_i32 s0, 0, 0x20210
	v_writelane_b32 v253, s0, 42
	s_add_i32 s0, 0, 0x20000
	v_writelane_b32 v253, s0, 43
	s_add_i32 s0, 0, 0x20020
	v_writelane_b32 v253, s0, 44
	s_add_i32 s0, 0, 0x20080
	v_writelane_b32 v253, s0, 45
	s_add_i32 s0, 0, 0x20090
	v_writelane_b32 v253, s0, 46
	s_add_i32 s0, 0, 0x20048
	v_writelane_b32 v253, s0, 47
	s_add_i32 s0, 0, 0x20028
	v_writelane_b32 v253, s0, 48
	s_add_i32 s0, 0, 0x20008
	v_writelane_b32 v253, s0, 49
	s_add_i32 s0, 0, 0x20010
	v_writelane_b32 v253, s0, 50
	s_add_i32 s0, 0, 0x20018
	v_writelane_b32 v253, s0, 51
	s_add_i32 s0, 0, 0x20058
	v_writelane_b32 v253, s0, 52
	s_add_i32 s0, 0, 0x20068
	v_writelane_b32 v253, s0, 53
	s_add_i32 s0, 0, 0x20078
	v_writelane_b32 v253, s0, 54
	s_add_i32 s0, 0, 0x200a0
	v_writelane_b32 v253, s0, 55
	s_add_i32 s0, 0, 0x200b0
	v_writelane_b32 v253, s0, 56
	s_add_i32 s0, 0, 0x200c0
	v_writelane_b32 v253, s0, 57
	s_add_i32 s0, 0, 0x20098
	v_writelane_b32 v253, s0, 58
	s_add_i32 s0, 0, 0x20040
	v_writelane_b32 v253, s0, 59
	s_add_i32 s0, 0, 0x20038
	v_writelane_b32 v253, s0, 60
	s_add_i32 s0, 0, 0x20030
	v_writelane_b32 v253, s0, 61
	s_add_i32 s0, 0, 0x20200
	v_writelane_b32 v253, s0, 62
	s_add_i32 s0, 0, 0x20204
	v_writelane_b32 v253, s0, 63
	s_mov_b32 s75, 0x3f000
	v_readlane_b32 s0, v253, 0
	s_mov_b32 s52, s0
	s_mov_b32 s27, 0
	v_cmp_eq_u32_e64 s[0:1], 0, v0
	s_mov_b64 s[70:71], 0x200
	s_mov_b64 s[50:51], 0x80
	v_writelane_b32 v254, s0, 0
	s_nop 1
	v_writelane_b32 v254, s1, 1
	s_lshl_b64 s[0:1], s[28:29], 7
	v_writelane_b32 v254, s0, 2
	s_nop 1
	v_writelane_b32 v254, s1, 3
	s_lshl_b64 s[0:1], s[28:29], 6
	v_writelane_b32 v254, s0, 4
	s_nop 1
	v_writelane_b32 v254, s1, 5
	s_lshl_b64 s[0:1], s[28:29], 2
	v_writelane_b32 v254, s0, 6
	s_nop 1
	v_writelane_b32 v254, s1, 7
	s_lshl_b64 s[0:1], s[28:29], 1
	v_writelane_b32 v254, s0, 8
	s_nop 1
	v_writelane_b32 v254, s1, 9
	v_writelane_b32 v254, s28, 10
	s_nop 1
	v_writelane_b32 v254, s29, 11
	v_writelane_b32 v254, s30, 12
	s_nop 1
	v_writelane_b32 v254, s31, 13
	v_writelane_b32 v254, s34, 14
	s_nop 1
	v_writelane_b32 v254, s35, 15
	v_writelane_b32 v254, s36, 16
	s_nop 1
	v_writelane_b32 v254, s37, 17
	v_writelane_b32 v254, s24, 18
	s_nop 1
	v_writelane_b32 v254, s25, 19
	v_writelane_b32 v254, s16, 20
	s_nop 1
	v_writelane_b32 v254, s17, 21
	v_writelane_b32 v254, s18, 22
	s_nop 1
	v_writelane_b32 v254, s19, 23
	v_writelane_b32 v254, s20, 24
	s_nop 1
	v_writelane_b32 v254, s21, 25
	v_writelane_b32 v254, s22, 26
	s_nop 1
	v_writelane_b32 v254, s23, 27
	v_writelane_b32 v254, s64, 28
	v_writelane_b32 v254, s26, 29
	v_writelane_b32 v254, s42, 30
	s_nop 1
	v_writelane_b32 v254, s43, 31
	v_writelane_b32 v254, s46, 32
	s_nop 1
	v_writelane_b32 v254, s47, 33
	v_writelane_b32 v254, s48, 34
	s_nop 1
	v_writelane_b32 v254, s49, 35
	v_writelane_b32 v254, s60, 36
	s_nop 1
	v_writelane_b32 v254, s61, 37
	v_writelane_b32 v254, s62, 38
	s_nop 1
	v_writelane_b32 v254, s63, 39
	v_writelane_b32 v254, s72, 40
	s_nop 1
	v_writelane_b32 v254, s73, 41
	v_writelane_b32 v254, s82, 42
	s_nop 1
	v_writelane_b32 v254, s83, 43
	v_writelane_b32 v254, s84, 44
	s_nop 1
	v_writelane_b32 v254, s85, 45
	v_writelane_b32 v254, s86, 46
	s_nop 1
	v_writelane_b32 v254, s87, 47
	v_writelane_b32 v254, s88, 48
	s_nop 1
	v_writelane_b32 v254, s89, 49
	s_mov_b32 s99, 0
	s_branch .LBB0_13

.LBB0_13:
	s_cmp_eq_u32 s44, s26
	s_cselect_b64 s[0:1], -1, 0
	s_and_b64 s[0:1], s[30:31], s[0:1]
	s_andn2_b64 vcc, exec, s[0:1]
	s_cbranch_vccnz .LBB0_17
	s_mov_b64 s[38:39], exec
	v_readlane_b32 s0, v253, 3
	v_readlane_b32 s1, v253, 4
	s_and_b64 s[0:1], s[38:39], s[0:1]
	s_mov_b64 exec, s[0:1]
	s_cbranch_execz .LBB0_16
	global_load_dword v0, v145, s[36:37] sc1
	global_load_dword v1, v145, s[24:25] sc1
	global_load_dword v2, v145, s[16:17] sc1
	global_load_dword v3, v145, s[18:19] sc1
	global_load_dword v4, v145, s[20:21] sc1
	global_load_dword v5, v145, s[22:23] sc1
	global_load_dword v6, v145, s[42:43] sc1
	global_load_dword v7, v145, s[46:47] sc1
	global_load_dword v8, v145, s[48:49] sc1
	global_load_dword v9, v145, s[60:61] sc1
	global_load_dword v10, v145, s[62:63] sc1
	global_load_dword v11, v145, s[72:73] sc1
	global_load_dword v12, v145, s[82:83] sc1
	global_load_dword v13, v145, s[84:85] sc1
	global_load_dword v14, v145, s[86:87] sc1
	global_load_dword v15, v145, s[88:89] sc1
	v_readlane_b32 s0, v253, 40
	v_readlane_b32 s16, v253, 9
	v_readlane_b32 s40, v253, 7
	v_mov_b32_e32 v16, s0
	v_readlane_b32 s0, v253, 41
	v_readlane_b32 s41, v253, 8
	s_waitcnt vmcnt(0)
	v_cmp_eq_u32_e64 s[4:5], s16, v1
	v_mov_b32_e32 v17, s0
	v_readlane_b32 s0, v253, 0
	s_waitcnt vmcnt(13)
	v_cmp_eq_u32_e64 s[6:7], s16, v2
	s_waitcnt vmcnt(12)
	v_cmp_eq_u32_e64 s[8:9], s16, v3
	v_mov_b32_e32 v18, s0
	v_cmp_eq_u32_e64 s[0:1], s16, v0
	s_and_b64 s[0:1], s[40:41], s[0:1]
	s_and_b64 s[0:1], s[0:1], s[4:5]
	s_and_b64 s[0:1], s[0:1], s[6:7]
	s_waitcnt vmcnt(11)
	v_cmp_eq_u32_e64 s[10:11], s16, v4
	s_and_b64 s[0:1], s[0:1], s[8:9]
	s_waitcnt vmcnt(10)
	v_cmp_eq_u32_e64 s[12:13], s16, v5
	s_and_b64 s[0:1], s[0:1], s[10:11]
	s_waitcnt vmcnt(9)
	v_cmp_eq_u32_e64 s[14:15], s16, v6
	s_and_b64 s[0:1], s[0:1], s[12:13]
	s_waitcnt vmcnt(8)
	v_cmp_eq_u32_e64 s[16:17], s16, v7
	s_and_b64 s[0:1], s[0:1], s[14:15]
	s_waitcnt vmcnt(7)
	v_cmp_eq_u32_e64 s[18:19], 0, v8
	s_and_b64 s[0:1], s[0:1], s[16:17]
	s_waitcnt vmcnt(6)
	v_cmp_eq_u32_e64 s[20:21], 0, v9
	s_and_b64 s[0:1], s[0:1], s[18:19]
	ds_read_b32 v16, v16
	ds_read_b32 v17, v17
	s_waitcnt vmcnt(5)
	v_cmp_eq_u32_e64 s[22:23], 0, v10
	s_and_b64 s[0:1], s[0:1], s[20:21]
	s_waitcnt vmcnt(4)
	v_cmp_eq_u32_e64 s[24:25], 0, v11
	s_and_b64 s[0:1], s[0:1], s[22:23]
	s_waitcnt vmcnt(3)
	v_cmp_eq_u32_e64 s[36:37], 0, v12
	s_and_b64 s[0:1], s[0:1], s[24:25]
	s_waitcnt vmcnt(2)
	v_cmp_eq_u32_e64 s[28:29], 0, v13
	s_and_b64 s[0:1], s[0:1], s[36:37]
	s_waitcnt lgkmcnt(1)
	v_lshlrev_b32_e32 v16, 3, v16
	s_waitcnt vmcnt(1)
	v_cmp_eq_u32_e64 s[30:31], 0, v14
	s_and_b64 s[0:1], s[0:1], s[28:29]
	s_waitcnt lgkmcnt(0)
	v_add_u32_e32 v16, v16, v17
	s_waitcnt vmcnt(0)
	v_cmp_eq_u32_e64 s[34:35], 0, v15
	s_and_b64 s[0:1], s[0:1], s[30:31]
	v_cmp_gt_u32_e32 vcc, s33, v16
	s_and_b64 s[0:1], s[0:1], s[34:35]
	v_readlane_b32 s20, v254, 24
	v_readlane_b32 s18, v254, 22
	v_readlane_b32 s16, v254, 20
	v_readlane_b32 s22, v254, 26
	v_readlane_b32 s24, v254, 18
	v_readlane_b32 s36, v254, 16
	v_readlane_b32 s30, v254, 12
	v_readlane_b32 s34, v254, 14
	v_readlane_b32 s28, v254, 10
	s_and_b64 vcc, s[0:1], vcc
	s_cselect_b32 s99, 1, 0
	s_cmpk_eq_i32 s33, 0x100
	s_cselect_b32 s99, s99, 0
	v_readlane_b32 s0, v253, 42
	v_readlane_b32 s21, v254, 25
	v_readlane_b32 s19, v254, 23
	v_readlane_b32 s17, v254, 21
	v_readlane_b32 s23, v254, 27
	v_readlane_b32 s25, v254, 19
	v_readlane_b32 s37, v254, 17
	v_readlane_b32 s31, v254, 13
	v_readlane_b32 s35, v254, 15
	v_readlane_b32 s29, v254, 11
	v_cndmask_b32_e32 v0, v18, v16, vcc
	v_mov_b32_e32 v1, s0
	ds_write_b32 v1, v0

.LBB0_17:
	s_mov_b64 s[62:63], s[78:79]
	s_add_u32 s0, s62, 0x10000000
	s_addc_u32 s1, s63, 0
	s_add_u32 s38, s62, 0x1c000000
	v_writelane_b32 v254, s0, 50
	s_addc_u32 s39, s63, 0
	s_nop 0
	v_writelane_b32 v254, s1, 51
	s_add_u32 s0, s62, 0x23c00000
	s_addc_u32 s1, s63, 0
	v_writelane_b32 v254, s0, 52
	s_cmpk_lt_i32 s44, 0x3e8
	s_nop 0
	v_writelane_b32 v254, s1, 53
	s_mov_b64 s[0:1], -1
	s_cbranch_scc0 .LBB0_744
	s_add_u32 s30, s62, 0xda00000
	s_addc_u32 s29, s63, 0
	s_add_u32 s42, s62, 0xe000000
	s_addc_u32 s43, s63, 0
	v_readlane_b32 s20, v253, 16
	s_mov_b64 s[6:7], -1
	s_mov_b64 s[4:5], 0
	s_cmp_lt_i32 s44, 1
	s_mov_b64 s[0:1], 0
	v_readlane_b32 s21, v253, 17
	v_readlane_b32 s31, v253, 37
	s_mul_i32 s34, s33, 24
	v_readlane_b32 s17, v253, 38
	v_readlane_b32 s22, v253, 39
	s_mov_b32 s35, 0x800000
	s_movk_i32 s23, 0x78
	s_cbranch_scc1 .LBB0_38
	s_cmp_eq_u32 s44, 1
	s_mov_b64 s[0:1], -1
	s_mov_b64 s[24:25], 0x1000
	s_cbranch_scc0 .LBB0_37
	v_mov_b32_e32 v186, v244
	v_readlane_b32 s8, v253, 10
	v_readfirstlane_b32 s0, v186
	s_ashr_i32 s16, s0, 6
	s_lshl_b32 s0, s52, 3
	s_cmpk_lg_i32 s33, 0x100
	s_cbranch_scc1 .Lrm_skipa
	s_and_b32 s0, s52, 7
	s_lshl_b32 s0, s0, 5
	s_lshr_b32 s1, s52, 3
	s_add_i32 s0, s0, s1
	s_lshl_b32 s0, s0, 3
.Lrm_skipa:
	s_add_i32 s16, s16, s0
	v_readlane_b32 s0, v253, 43
	s_add_u32 s6, s62, 0x24400000
	v_readlane_b32 s9, v253, 11
	v_mov_b32_e32 v0, s0
	v_readlane_b32 s0, v253, 44
	v_and_b32_e32 v69, 63, v186
	s_addc_u32 s7, s63, 0
	v_mov_b32_e32 v1, s0
	s_waitcnt lgkmcnt(0)
	ds_read_b64 v[66:67], v0
	ds_read_b64 v[64:65], v1
	s_mov_b64 s[0:1], -1
	s_and_b64 vcc, exec, s[8:9]
	s_cbranch_vccz .LBB0_29
	s_waitcnt lgkmcnt(0)
	v_readfirstlane_b32 s1, v67
	v_readfirstlane_b32 s0, v66
	s_waitcnt lgkmcnt(0)
	v_readfirstlane_b32 s9, v65
	s_cmpk_gt_i32 s16, 0x3fff
	v_readfirstlane_b32 s8, v64
	s_cbranch_scc1 .LBB0_28
	v_lshlrev_b32_e32 v68, 2, v69
	v_lshlrev_b32_e32 v144, 4, v69
	v_xor_b32_e32 v75, 4, v68
	v_xor_b32_e32 v80, 8, v68
	v_xor_b32_e32 v81, 16, v68
	v_xor_b32_e32 v82, 32, v68
	v_xor_b32_e32 v83, 64, v68
	v_xor_b32_e32 v84, 0x80, v68
	v_lshl_add_u64 v[70:71], s[8:9], 0, v[144:145]
	v_lshl_add_u64 v[72:73], s[0:1], 0, v[144:145]
	v_lshlrev_b32_e32 v144, 2, v68
	s_mov_b32 s14, s16
	s_branch .LBB0_24

.LBB0_472:
	s_and_b64 vcc, exec, s[0:1]
	s_cbranch_vccz .LBB0_679
	v_readlane_b32 s0, v254, 57
	v_readlane_b32 s1, v254, 58
	s_mov_b32 s14, s0
	s_mul_i32 s1, s14, 0x48000
	v_readlane_b32 s12, v254, 55
	s_mul_hi_i32 s0, s0, 0x48000
	s_add_u32 s26, s12, s1
	v_readlane_b32 s13, v254, 56
	v_mov_b32_e32 v0, v244
	s_addc_u32 s28, s13, s0
	v_readlane_b32 s57, v254, 54
	v_readfirstlane_b32 s0, v0
	s_ashr_i32 s24, s0, 6
	s_lshl_b32 s0, s52, 3
	s_cmpk_lg_i32 s33, 0x100
	s_cbranch_scc1 .Lrm_skipb
	s_and_b32 s0, s52, 7
	s_lshl_b32 s0, s0, 5
	s_lshr_b32 s1, s52, 3
	s_add_i32 s0, s0, s1
	s_lshl_b32 s0, s0, 3
.Lrm_skipb:
	s_add_i32 s24, s24, s0
	s_cmp_eq_u32 s41, 7
	s_cselect_b64 s[0:1], -1, 0
	v_cndmask_b32_e64 v48, 0.5, 1.0, s[0:1]
	s_and_b64 s[0:1], s[0:1], exec
	s_cselect_b32 s0, 1, 2
	s_cmp_lg_u32 s41, 2
	s_cselect_b32 s25, s0, 0
	s_sub_i32 s0, s44, 35
	s_cmp_lt_u32 s0, 11
	s_cselect_b64 s[0:1], -1, 0
	s_add_i32 s8, s25, 1
	s_cmp_eq_u32 s41, 10
	s_cselect_b64 s[6:7], -1, 0
	s_and_b64 s[4:5], s[6:7], exec
	s_cselect_b32 s8, 0, s8
	s_and_b64 s[0:1], s[0:1], s[6:7]
	s_xor_b64 s[10:11], s[0:1], -1
	s_xor_b64 s[6:7], s[6:7], s[0:1]
	s_cmp_lg_u64 s[6:7], 0
	s_addc_u32 s6, s14, 0
	s_mul_i32 s9, s6, 0x48000
	s_add_u32 s9, s12, s9
	v_readlane_b32 s12, v253, 44
	v_and_b32_e32 v116, 63, v0
	s_mul_hi_i32 s7, s6, 0x48000
	v_mov_b32_e32 v0, s12
	ds_read_b64 v[0:1], v0
	s_addc_u32 s7, s13, s7
	s_mul_i32 s12, s8, 0x3000
	s_add_u32 s29, s9, s12
	s_mul_i32 s6, s6, 3
	s_addc_u32 s30, s7, 0
	s_add_i32 s6, s6, s8
	s_ashr_i32 s7, s6, 31
	s_waitcnt lgkmcnt(0)
	v_readfirstlane_b32 s12, v0
	s_lshl_b64 s[6:7], s[6:7], 12
	v_readfirstlane_b32 s9, v1
	s_add_u32 s12, s12, s6
	s_addc_u32 s13, s9, s7
	s_add_u32 s8, s62, 0x24400000
	s_addc_u32 s9, s63, 0
	s_and_b64 s[0:1], s[0:1], exec
	v_readlane_b32 s0, v253, 5
	v_readlane_b32 s6, v253, 10
	v_readlane_b32 s1, v253, 6
	v_readlane_b32 s7, v253, 11
	s_mov_b64 s[4:5], -1
	s_cselect_b32 s1, s1, 0
	s_cselect_b32 s0, s0, 0
	s_and_b64 vcc, exec, s[6:7]
	s_cbranch_vccz .LBB0_553
	v_readlane_b32 s4, v253, 48
	s_cmpk_gt_i32 s24, 0x3fff
	s_mov_b64 s[36:37], 0x1000
	v_mov_b32_e32 v0, s4
	ds_read_b64 v[0:1], v0
	s_waitcnt lgkmcnt(0)
	v_readfirstlane_b32 s4, v1
	v_readfirstlane_b32 s5, v0
	s_cbranch_scc1 .LBB0_552
	v_readlane_b32 s6, v254, 57
	s_mul_i32 s6, s6, 3
	v_readlane_b32 s7, v254, 58
	s_add_i32 s6, s25, s6
	s_ashr_i32 s7, s6, 31
	s_lshl_b64 s[6:7], s[6:7], 12
	s_add_u32 s6, s5, s6
	s_addc_u32 s7, s4, s7
	s_mul_i32 s4, s25, 0x3000
	s_add_u32 s4, s26, s4
	s_addc_u32 s5, s28, 0
	v_lshlrev_b32_e32 v144, 4, v116
	v_lshlrev_b32_e32 v28, 2, v116
	v_lshl_add_u64 v[0:1], s[4:5], 0, v[144:145]
	s_mov_b64 s[4:5], 0x2000
	s_cmp_lg_u64 s[0:1], 0
	v_xor_b32_e32 v29, 4, v28
	v_xor_b32_e32 v117, 8, v28
	v_xor_b32_e32 v118, 16, v28
	v_xor_b32_e32 v119, 32, v28
	v_xor_b32_e32 v120, 64, v28
	v_xor_b32_e32 v121, 0x80, v28
	v_lshl_add_u64 v[30:31], s[6:7], 0, v[144:145]
	v_lshl_add_u64 v[32:33], v[0:1], 0, s[4:5]
	v_mov_b32_e32 v34, v48
	v_mov_b32_e32 v35, v48
	s_cselect_b64 s[14:15], -1, 0
	v_lshl_add_u64 v[36:37], s[12:13], 0, v[144:145]
	s_mov_b32 s4, s24
	s_branch .LBB0_477

.LBB0_816:
	s_andn2_saveexec_b64 s[8:9], s[8:9]
	s_cbranch_execz .LBB0_11
	s_mov_b64 s[8:9], exec
	s_cmp_eq_u32 s99, 0
	s_cbranch_scc1 .Lxb_global
	s_add_i32 s10, s44, -3
	s_cmp_lt_i32 s10, 0
	s_cbranch_scc1 .Lxb_global
	s_mul_i32 s11, s10, 47
	s_lshr_b32 s11, s11, 9
	s_mul_i32 s11, s11, 11
	s_sub_i32 s10, s10, s11
	s_lshl_b32 s10, 1, s10
	s_and_b32 s10, s10, 0x3e7
	s_cmp_lg_u32 s10, 0
	s_cbranch_scc1 .LBB0_833
.Lxb_global:
	buffer_wbl2 sc1
	s_waitcnt lgkmcnt(0)
	s_waitcnt vmcnt(0)
	v_mbcnt_lo_u32_b32 v1, s8, 0
	v_mbcnt_hi_u32_b32 v1, s9, v1
	v_cmp_eq_u32_e32 vcc, 0, v1
	s_and_saveexec_b64 s[10:11], vcc
	s_cbranch_execz .LBB0_819
	s_bcnt1_i32_b64 s8, s[8:9]
	v_mov_b32_e32 v2, s8
	v_readlane_b32 s8, v253, 26
	v_readlane_b32 s9, v253, 27
	s_nop 4
	global_atomic_add v2, v145, v2, s[8:9] sc0
